# att: next row's selection list written to LDS and its 32 K/V row offsets computed during PV steps 3-5 of the current row, so a row starts by issuing its K loads immediately
# baseline (speedup 1.0000x reference)
.LBB0_1249:
	s_or_b64 exec, exec, s[8:9]
	v_readfirstlane_b32 s8, v0
	s_cmp_gt_i32 s8, 0x101ff
	s_cbranch_scc1 .LBB0_1298
	s_add_u32 s22, s10, 0x3700000
	s_addc_u32 s23, s11, 0
	s_add_u32 s24, s10, 0x4800000
	s_addc_u32 s25, s11, 0
	s_add_u32 s26, s10, 0x32e00000
	s_addc_u32 s27, s11, 0
	s_add_u32 s31, s10, 0x34e00000
	s_addc_u32 s36, s11, 0
	s_add_u32 s37, s10, 0x16a00000
	s_addc_u32 s38, s11, 0
	s_add_u32 s39, s10, 0x37a00000
	s_addc_u32 s40, s11, 0
	s_lshl_b32 s9, s19, 4
	v_mbcnt_hi_u32_b32 v0, -1, v182
	s_add_i32 s41, s9, 0
	v_lshlrev_b32_e32 v0, 2, v0
	s_mov_b32 s15, 0
	s_add_i32 s41, s41, 0x21000
	v_mov_b32_e32 v113, 0
	s_lshl_b32 s42, s18, 1
	s_mov_b32 s43, 0x1fffe00
	s_movk_i32 s44, 0xa0
	s_mov_b32 s45, 0xffffff
	s_mov_b32 s46, 0xff61b1e6
	v_and_b32_e32 v114, 0x100, v0
	s_lshl_b32 s14, s3, 1
	s_ashr_i32 s9, s8, 31
	s_lshl_b64 s[100:101], s[8:9], 10
	s_add_u32 s100, s39, s100
	s_addc_u32 s101, s40, s101
	v_and_b32_e32 v204, 63, v194
	v_lshlrev_b32_e32 v204, 4, v204
	global_load_dwordx4 v[204:207], v204, s[100:101]
	s_waitcnt vmcnt(0)
	v_readfirstlane_b32 s100, v194
	s_lshr_b32 s100, s100, 6
	s_mulk_i32 s100, 0x1800
	s_add_i32 s47, s100, 0
	v_and_b32_e32 v117, 63, v194
	v_lshrrev_b32_e32 v122, 3, v117
	v_lshl_add_u32 v119, v122, 2, s47
	v_lshlrev_b32_e32 v118, 4, v194
	v_and_b32_e32 v118, 0x70, v118
	v_lshl_add_u32 v134, v117, 4, s47
	ds_write_b128 v134, v[204:207]
	ds_read2_b32 v[136:137], v119 offset1:8
	ds_read2_b32 v[138:139], v119 offset0:16 offset1:24
	ds_read2_b32 v[140:141], v119 offset0:32 offset1:40
	ds_read2_b32 v[142:143], v119 offset0:48 offset1:56
	ds_read2_b32 v[144:145], v119 offset0:64 offset1:72
	ds_read2_b32 v[146:147], v119 offset0:80 offset1:88
	ds_read2_b32 v[148:149], v119 offset0:96 offset1:104
	ds_read2_b32 v[150:151], v119 offset0:112 offset1:120
	ds_read2_b32 v[152:153], v119 offset0:128 offset1:136
	ds_read2_b32 v[154:155], v119 offset0:144 offset1:152
	ds_read2_b32 v[156:157], v119 offset0:160 offset1:168
	ds_read2_b32 v[158:159], v119 offset0:176 offset1:184
	ds_read2_b32 v[160:161], v119 offset0:192 offset1:200
	ds_read2_b32 v[162:163], v119 offset0:208 offset1:216
	ds_read2_b32 v[164:165], v119 offset0:224 offset1:232
	ds_read2_b32 v[166:167], v119 offset0:240 offset1:248
	s_waitcnt lgkmcnt(0)
	v_lshlrev_b32_e32 v136, 9, v136
	v_lshlrev_b32_e32 v137, 9, v137
	v_and_or_b32 v208, v136, s43, v118
	v_and_or_b32 v209, v137, s43, v118
	v_lshlrev_b32_e32 v138, 9, v138
	v_lshlrev_b32_e32 v139, 9, v139
	v_and_or_b32 v210, v138, s43, v118
	v_and_or_b32 v211, v139, s43, v118
	v_lshlrev_b32_e32 v140, 9, v140
	v_lshlrev_b32_e32 v141, 9, v141
	v_and_or_b32 v212, v140, s43, v118
	v_and_or_b32 v213, v141, s43, v118
	v_lshlrev_b32_e32 v142, 9, v142
	v_lshlrev_b32_e32 v143, 9, v143
	v_and_or_b32 v214, v142, s43, v118
	v_and_or_b32 v215, v143, s43, v118
	v_lshlrev_b32_e32 v144, 9, v144
	v_lshlrev_b32_e32 v145, 9, v145
	v_and_or_b32 v216, v144, s43, v118
	v_and_or_b32 v217, v145, s43, v118
	v_lshlrev_b32_e32 v146, 9, v146
	v_lshlrev_b32_e32 v147, 9, v147
	v_and_or_b32 v218, v146, s43, v118
	v_and_or_b32 v219, v147, s43, v118
	v_lshlrev_b32_e32 v148, 9, v148
	v_lshlrev_b32_e32 v149, 9, v149
	v_and_or_b32 v220, v148, s43, v118
	v_and_or_b32 v221, v149, s43, v118
	v_lshlrev_b32_e32 v150, 9, v150
	v_lshlrev_b32_e32 v151, 9, v151
	v_and_or_b32 v222, v150, s43, v118
	v_and_or_b32 v223, v151, s43, v118
	v_lshlrev_b32_e32 v152, 9, v152
	v_lshlrev_b32_e32 v153, 9, v153
	v_and_or_b32 v224, v152, s43, v118
	v_and_or_b32 v225, v153, s43, v118
	v_lshlrev_b32_e32 v154, 9, v154
	v_lshlrev_b32_e32 v155, 9, v155
	v_and_or_b32 v226, v154, s43, v118
	v_and_or_b32 v227, v155, s43, v118
	v_lshlrev_b32_e32 v156, 9, v156
	v_lshlrev_b32_e32 v157, 9, v157
	v_and_or_b32 v228, v156, s43, v118
	v_and_or_b32 v229, v157, s43, v118
	v_lshlrev_b32_e32 v158, 9, v158
	v_lshlrev_b32_e32 v159, 9, v159
	v_and_or_b32 v230, v158, s43, v118
	v_and_or_b32 v231, v159, s43, v118
	v_lshlrev_b32_e32 v160, 9, v160
	v_lshlrev_b32_e32 v161, 9, v161
	v_and_or_b32 v232, v160, s43, v118
	v_and_or_b32 v233, v161, s43, v118
	v_lshlrev_b32_e32 v162, 9, v162
	v_lshlrev_b32_e32 v163, 9, v163
	v_and_or_b32 v234, v162, s43, v118
	v_and_or_b32 v235, v163, s43, v118
	v_lshlrev_b32_e32 v164, 9, v164
	v_lshlrev_b32_e32 v165, 9, v165
	v_and_or_b32 v236, v164, s43, v118
	v_and_or_b32 v237, v165, s43, v118
	v_lshlrev_b32_e32 v166, 9, v166
	v_lshlrev_b32_e32 v167, 9, v167
	v_and_or_b32 v238, v166, s43, v118
	v_and_or_b32 v239, v167, s43, v118
	s_branch .LBB0_1252

.LBB0_1260:
	s_lshr_b32 s9, s9, 6
	s_mulk_i32 s9, 0x1800
	s_add_i32 s47, s9, 0
	s_ashr_i32 s9, s8, 31
	s_lshl_b64 s[16:17], s[8:9], 10
	v_and_b32_e32 v117, 63, v120
	s_add_u32 s16, s39, s16
	s_addc_u32 s17, s40, s17
	v_and_b32_e32 v116, 15, v120
	s_lshl_b64 s[8:9], s[8:9], 11
	v_lshlrev_b32_e32 v4, 6, v116
	s_add_u32 s16, s37, s8
	v_add_lshl_u32 v112, v4, s3, 1
	s_addc_u32 s17, s38, s9
	v_lshl_add_u64 v[4:5], s[16:17], 0, v[112:113]
	v_and_b32_e32 v112, 48, v120
	v_mov_b32_e32 v56, 0
	v_mov_b32_e32 v0, 0
	v_mov_b32_e32 v1, 0
	v_mov_b32_e32 v2, 0
	v_cmp_gt_u32_e32 vcc, 4, v116
	v_lshl_add_u64 v[4:5], v[4:5], 0, v[112:113]
	v_mov_b32_e32 v3, 0
	s_and_saveexec_b64 s[8:9], vcc
	s_cbranch_execz .LBB0_1262
	global_load_dwordx4 v[0:3], v[4:5], off

.LBB0_1264:
	s_or_b64 exec, exec, s[8:9]
	v_lshrrev_b32_e32 v122, 3, v117
	v_lshl_add_u32 v119, v122, 2, s47
	s_waitcnt lgkmcnt(0)
	v_lshlrev_b32_e32 v6, 4, v120
	s_add_u32 s8, s20, s42
	v_and_b32_e32 v118, 0x70, v6
	s_addc_u32 s9, s21, 0
	global_load_dwordx4 v[4:7], v208, s[8:9]
	s_nop 0
	global_load_dwordx4 v[8:11], v209, s[8:9]
	global_load_dwordx4 v[12:15], v210, s[8:9]
	s_nop 0
	global_load_dwordx4 v[16:19], v211, s[8:9]
	s_add_u32 s18, s18, s42
	s_addc_u32 s19, s19, 0
	global_load_dwordx4 v[20:23], v212, s[8:9]
	s_nop 0
	global_load_dwordx4 v[24:27], v213, s[8:9]
	global_load_dwordx4 v[28:31], v214, s[8:9]
	s_nop 0
	global_load_dwordx4 v[32:35], v215, s[8:9]
	global_load_dwordx4 v[36:39], v216, s[8:9]
	s_nop 0
	global_load_dwordx4 v[40:43], v217, s[8:9]
	s_nop 0
	global_load_dwordx4 v[44:47], v218, s[8:9]
	s_nop 0
	global_load_dwordx4 v[48:51], v219, s[8:9]
	v_add_u32_e32 v112, s47, v112
	v_add_u32_e32 v121, s47, v118
	v_mad_u32_u24 v123, v116, s44, v112
	global_load_dwordx4 v[52:55], v220, s[8:9]
	s_nop 0
	global_load_dwordx4 v[60:63], v221, s[8:9]
	s_nop 0
	global_load_dwordx4 v[64:67], v222, s[8:9]
	s_nop 0
	global_load_dwordx4 v[68:71], v223, s[8:9]
	s_and_saveexec_b64 s[98:99], s[6:7]
	v_mov_b32_e32 v200, 1
	global_atomic_add v200, v113, v200, s[12:13] sc0
	s_or_b64 exec, exec, s[98:99]
	v_mad_u32_u24 v132, v122, s44, v121
	s_waitcnt vmcnt(15)
	ds_write_b128 v132, v[4:7] offset:1024
	s_waitcnt vmcnt(14)
	ds_write_b128 v132, v[8:11] offset:2304
	s_waitcnt vmcnt(13)
	ds_write_b128 v132, v[12:15] offset:3584
	s_waitcnt vmcnt(12)
	ds_write_b128 v132, v[16:19] offset:4864
	ds_read_b128 v[4:7], v123 offset:1024
	ds_read_b128 v[8:11], v123 offset:1088
	ds_read_b128 v[12:15], v123 offset:3584
	ds_read_b128 v[16:19], v123 offset:3648
	s_waitcnt lgkmcnt(3)
	v_mfma_f32_16x16x32_bf16 v[4:7], v[4:7], v[0:3], 0
	s_waitcnt lgkmcnt(0)
	v_mfma_f32_16x16x32_bf16 v[108:111], v[8:11], v[56:59], v[4:7]
	v_mfma_f32_16x16x32_bf16 v[12:15], v[12:15], v[0:3], 0
	s_nop 4
	global_load_dwordx4 v[4:7], v224, s[8:9]
	s_nop 0
	global_load_dwordx4 v[8:11], v225, s[8:9]
	s_nop 0
	global_load_dwordx4 v[72:75], v226, s[8:9]
	s_nop 0
	global_load_dwordx4 v[76:79], v227, s[8:9]
	v_mfma_f32_16x16x32_bf16 v[104:107], v[16:19], v[56:59], v[12:15]
	s_waitcnt vmcnt(15)
	ds_write_b128 v132, v[20:23] offset:1024
	s_waitcnt vmcnt(14)
	ds_write_b128 v132, v[24:27] offset:2304
	s_waitcnt vmcnt(13)
	ds_write_b128 v132, v[28:31] offset:3584
	s_waitcnt vmcnt(12)
	ds_write_b128 v132, v[32:35] offset:4864
	ds_read_b128 v[12:15], v123 offset:1024
	ds_read_b128 v[16:19], v123 offset:1088
	ds_read_b128 v[20:23], v123 offset:3584
	ds_read_b128 v[24:27], v123 offset:3648
	s_waitcnt lgkmcnt(3)
	v_mfma_f32_16x16x32_bf16 v[12:15], v[12:15], v[0:3], 0
	s_waitcnt lgkmcnt(0)
	v_mfma_f32_16x16x32_bf16 v[100:103], v[16:19], v[56:59], v[12:15]
	v_mfma_f32_16x16x32_bf16 v[20:23], v[20:23], v[0:3], 0
	s_nop 4
	global_load_dwordx4 v[12:15], v228, s[8:9]
	s_nop 0
	global_load_dwordx4 v[16:19], v229, s[8:9]
	s_nop 0
	global_load_dwordx4 v[28:31], v230, s[8:9]
	s_nop 0
	global_load_dwordx4 v[32:35], v231, s[8:9]
	v_mfma_f32_16x16x32_bf16 v[96:99], v[24:27], v[56:59], v[20:23]
	s_waitcnt vmcnt(15)
	ds_write_b128 v132, v[36:39] offset:1024
	s_waitcnt vmcnt(14)
	ds_write_b128 v132, v[40:43] offset:2304
	s_waitcnt vmcnt(13)
	ds_write_b128 v132, v[44:47] offset:3584
	s_waitcnt vmcnt(12)
	ds_write_b128 v132, v[48:51] offset:4864
	ds_read_b128 v[20:23], v123 offset:1024
	ds_read_b128 v[24:27], v123 offset:1088
	ds_read_b128 v[36:39], v123 offset:3584
	ds_read_b128 v[40:43], v123 offset:3648
	s_waitcnt lgkmcnt(3)
	v_mfma_f32_16x16x32_bf16 v[20:23], v[20:23], v[0:3], 0
	s_waitcnt lgkmcnt(0)
	v_mfma_f32_16x16x32_bf16 v[92:95], v[24:27], v[56:59], v[20:23]
	v_mfma_f32_16x16x32_bf16 v[36:39], v[36:39], v[0:3], 0
	s_nop 4
	global_load_dwordx4 v[20:23], v232, s[8:9]
	s_nop 0
	global_load_dwordx4 v[24:27], v233, s[8:9]
	s_nop 0
	global_load_dwordx4 v[44:47], v234, s[8:9]
	s_nop 0
	global_load_dwordx4 v[48:51], v235, s[8:9]
	v_mfma_f32_16x16x32_bf16 v[88:91], v[40:43], v[56:59], v[36:39]
	s_waitcnt vmcnt(15)
	ds_write_b128 v132, v[52:55] offset:1024
	s_waitcnt vmcnt(14)
	ds_write_b128 v132, v[60:63] offset:2304
	s_waitcnt vmcnt(13)
	ds_write_b128 v132, v[64:67] offset:3584
	s_waitcnt vmcnt(12)
	ds_write_b128 v132, v[68:71] offset:4864
	ds_read_b128 v[36:39], v123 offset:1024
	ds_read_b128 v[40:43], v123 offset:1088
	ds_read_b128 v[52:55], v123 offset:3584
	ds_read_b128 v[60:63], v123 offset:3648
	s_waitcnt lgkmcnt(3)
	v_mfma_f32_16x16x32_bf16 v[36:39], v[36:39], v[0:3], 0
	s_waitcnt lgkmcnt(0)
	v_mfma_f32_16x16x32_bf16 v[84:87], v[40:43], v[56:59], v[36:39]
	v_mfma_f32_16x16x32_bf16 v[52:55], v[52:55], v[0:3], 0
	s_nop 4
	global_load_dwordx4 v[36:39], v236, s[8:9]
	s_nop 0
	global_load_dwordx4 v[40:43], v237, s[8:9]
	global_load_dwordx4 v[124:127], v238, s[8:9]
	global_load_dwordx4 v[128:131], v239, s[8:9]
	v_mfma_f32_16x16x32_bf16 v[80:83], v[60:63], v[56:59], v[52:55]
	s_waitcnt vmcnt(15)
	ds_write_b128 v132, v[4:7] offset:1024
	s_waitcnt vmcnt(14)
	ds_write_b128 v132, v[8:11] offset:2304
	s_waitcnt vmcnt(13)
	ds_write_b128 v132, v[72:75] offset:3584
	s_waitcnt vmcnt(12)
	ds_write_b128 v132, v[76:79] offset:4864
	ds_read_b128 v[4:7], v123 offset:1024
	ds_read_b128 v[8:11], v123 offset:1088
	ds_read_b128 v[52:55], v123 offset:3584
	ds_read_b128 v[60:63], v123 offset:3648
	s_waitcnt lgkmcnt(3)
	v_mfma_f32_16x16x32_bf16 v[4:7], v[4:7], v[0:3], 0
	s_waitcnt lgkmcnt(1)
	v_mfma_f32_16x16x32_bf16 v[52:55], v[52:55], v[0:3], 0
	v_mfma_f32_16x16x32_bf16 v[76:79], v[8:11], v[56:59], v[4:7]
	s_waitcnt lgkmcnt(0)
	v_mfma_f32_16x16x32_bf16 v[72:75], v[60:63], v[56:59], v[52:55]
	s_waitcnt vmcnt(11)
	ds_write_b128 v132, v[12:15] offset:1024
	s_waitcnt vmcnt(10)
	ds_write_b128 v132, v[16:19] offset:2304
	s_waitcnt vmcnt(9)
	ds_write_b128 v132, v[28:31] offset:3584
	s_waitcnt vmcnt(8)
	ds_write_b128 v132, v[32:35] offset:4864
	ds_read_b128 v[4:7], v123 offset:1024
	ds_read_b128 v[8:11], v123 offset:1088
	ds_read_b128 v[12:15], v123 offset:3584
	ds_read_b128 v[16:19], v123 offset:3648
	s_waitcnt lgkmcnt(3)
	v_mfma_f32_16x16x32_bf16 v[4:7], v[4:7], v[0:3], 0
	s_waitcnt lgkmcnt(1)
	v_mfma_f32_16x16x32_bf16 v[12:15], v[12:15], v[0:3], 0
	v_mfma_f32_16x16x32_bf16 v[68:71], v[8:11], v[56:59], v[4:7]
	s_waitcnt lgkmcnt(0)
	v_mfma_f32_16x16x32_bf16 v[64:67], v[16:19], v[56:59], v[12:15]
	s_waitcnt vmcnt(7)
	ds_write_b128 v132, v[20:23] offset:1024
	s_waitcnt vmcnt(6)
	ds_write_b128 v132, v[24:27] offset:2304
	s_waitcnt vmcnt(5)
	ds_write_b128 v132, v[44:47] offset:3584
	s_waitcnt vmcnt(4)
	ds_write_b128 v132, v[48:51] offset:4864
	ds_read_b128 v[4:7], v123 offset:1024
	ds_read_b128 v[8:11], v123 offset:1088
	ds_read_b128 v[12:15], v123 offset:3584
	ds_read_b128 v[16:19], v123 offset:3648
	s_waitcnt lgkmcnt(3)
	v_mfma_f32_16x16x32_bf16 v[4:7], v[4:7], v[0:3], 0
	s_waitcnt lgkmcnt(1)
	v_mfma_f32_16x16x32_bf16 v[12:15], v[12:15], v[0:3], 0
	v_mfma_f32_16x16x32_bf16 v[60:63], v[8:11], v[56:59], v[4:7]
	s_waitcnt lgkmcnt(0)
	v_mfma_f32_16x16x32_bf16 v[52:55], v[16:19], v[56:59], v[12:15]
	s_waitcnt vmcnt(3)
	ds_write_b128 v132, v[36:39] offset:1024
	s_waitcnt vmcnt(2)
	ds_write_b128 v132, v[40:43] offset:2304
	s_waitcnt vmcnt(1)
	ds_write_b128 v132, v[124:127] offset:3584
	s_waitcnt vmcnt(0)
	ds_write_b128 v132, v[128:131] offset:4864
	v_readfirstlane_b32 s100, v200
	s_ashr_i32 s101, s100, 31
	s_lshl_b64 s[100:101], s[100:101], 10
	s_add_u32 s100, s39, s100
	s_addc_u32 s101, s40, s101
	v_lshlrev_b32_e32 v204, 4, v117
	global_load_dwordx4 v[204:207], v204, s[100:101]
	ds_read_b128 v[4:7], v123 offset:1024
	ds_read_b128 v[8:11], v123 offset:1088
	ds_read_b128 v[12:15], v123 offset:3584
	ds_read_b128 v[124:127], v123 offset:3648
	s_waitcnt lgkmcnt(3)
	v_mfma_f32_16x16x32_bf16 v[4:7], v[4:7], v[0:3], 0
	s_waitcnt lgkmcnt(1)
	v_mfma_f32_16x16x32_bf16 v[128:131], v[12:15], v[0:3], 0
	s_waitcnt lgkmcnt(0)
	global_load_dwordx4 v[32:35], v208, s[18:19]
	global_load_dwordx4 v[36:39], v209, s[18:19]
	global_load_dwordx4 v[40:43], v210, s[18:19]
	global_load_dwordx4 v[44:47], v211, s[18:19]
	global_load_dwordx4 v[16:19], v212, s[18:19]
	global_load_dwordx4 v[20:23], v213, s[18:19]
	v_mfma_f32_16x16x32_bf16 v[48:51], v[8:11], v[56:59], v[4:7]
	global_load_dwordx4 v[24:27], v214, s[18:19]
	global_load_dwordx4 v[28:31], v215, s[18:19]
	v_mfma_f32_16x16x32_bf16 v[56:59], v[124:127], v[56:59], v[128:131]
	global_load_dwordx4 v[0:3], v216, s[18:19]
	s_nop 0
	global_load_dwordx4 v[4:7], v217, s[18:19]
	s_nop 0
	global_load_dwordx4 v[8:11], v218, s[18:19]
	s_nop 0
	global_load_dwordx4 v[12:15], v219, s[18:19]
	v_and_b32_e32 v123, 12, v116
	v_add_u32_e32 v123, v112, v123
	v_and_b32_e32 v112, 3, v120
	v_lshl_add_u32 v112, v112, 2, s41
	ds_read_b32 v136, v123
	ds_read_b32 v137, v123 offset:64
	ds_read_b32 v138, v123 offset:128
	ds_read_b32 v139, v123 offset:192
	ds_read_b32 v140, v123 offset:256
	ds_read_b32 v141, v123 offset:320
	ds_read_b32 v142, v123 offset:384
	ds_read_b32 v143, v123 offset:448
	ds_read_b32 v144, v123 offset:512
	ds_read_b32 v145, v123 offset:576
	ds_read_b32 v146, v123 offset:640
	ds_read_b32 v147, v123 offset:704
	ds_read_b32 v148, v123 offset:768
	ds_read_b32 v149, v123 offset:832
	ds_read_b32 v150, v123 offset:896
	ds_read_b32 v151, v123 offset:960
	s_movk_i32 s8, 0x7c0
	v_mov_b32_e32 v168, 0xf149f2ca
	v_mov_b32_dpp v108, v109 row_shr:4 row_mask:0xf bank_mask:0x2
	v_mov_b32_dpp v104, v105 row_shr:4 row_mask:0xf bank_mask:0x2
	v_mov_b32_dpp v100, v101 row_shr:4 row_mask:0xf bank_mask:0x2
	v_mov_b32_dpp v96, v97 row_shr:4 row_mask:0xf bank_mask:0x2
	v_mov_b32_dpp v92, v93 row_shr:4 row_mask:0xf bank_mask:0x2
	v_mov_b32_dpp v88, v89 row_shr:4 row_mask:0xf bank_mask:0x2
	v_mov_b32_dpp v84, v85 row_shr:4 row_mask:0xf bank_mask:0x2
	v_mov_b32_dpp v80, v81 row_shr:4 row_mask:0xf bank_mask:0x2
	v_mov_b32_dpp v76, v77 row_shr:4 row_mask:0xf bank_mask:0x2
	v_mov_b32_dpp v72, v73 row_shr:4 row_mask:0xf bank_mask:0x2
	v_mov_b32_dpp v68, v69 row_shr:4 row_mask:0xf bank_mask:0x2
	v_mov_b32_dpp v64, v65 row_shr:4 row_mask:0xf bank_mask:0x2
	v_mov_b32_dpp v60, v61 row_shr:4 row_mask:0xf bank_mask:0x2
	v_mov_b32_dpp v52, v53 row_shr:4 row_mask:0xf bank_mask:0x2
	v_mov_b32_dpp v48, v49 row_shr:4 row_mask:0xf bank_mask:0x2
	v_mov_b32_dpp v56, v57 row_shr:4 row_mask:0xf bank_mask:0x2
	v_mov_b32_dpp v108, v110 row_shr:8 row_mask:0xf bank_mask:0x4
	v_mov_b32_dpp v104, v106 row_shr:8 row_mask:0xf bank_mask:0x4
	v_mov_b32_dpp v100, v102 row_shr:8 row_mask:0xf bank_mask:0x4
	v_mov_b32_dpp v96, v98 row_shr:8 row_mask:0xf bank_mask:0x4
	v_mov_b32_dpp v92, v94 row_shr:8 row_mask:0xf bank_mask:0x4
	v_mov_b32_dpp v88, v90 row_shr:8 row_mask:0xf bank_mask:0x4
	v_mov_b32_dpp v84, v86 row_shr:8 row_mask:0xf bank_mask:0x4
	v_mov_b32_dpp v80, v82 row_shr:8 row_mask:0xf bank_mask:0x4
	v_mov_b32_dpp v76, v78 row_shr:8 row_mask:0xf bank_mask:0x4
	v_mov_b32_dpp v72, v74 row_shr:8 row_mask:0xf bank_mask:0x4
	v_mov_b32_dpp v68, v70 row_shr:8 row_mask:0xf bank_mask:0x4
	v_mov_b32_dpp v64, v66 row_shr:8 row_mask:0xf bank_mask:0x4
	v_mov_b32_dpp v60, v62 row_shr:8 row_mask:0xf bank_mask:0x4
	v_mov_b32_dpp v52, v54 row_shr:8 row_mask:0xf bank_mask:0x4
	v_mov_b32_dpp v48, v50 row_shr:8 row_mask:0xf bank_mask:0x4
	v_mov_b32_dpp v56, v58 row_shr:8 row_mask:0xf bank_mask:0x4
	v_mov_b32_dpp v108, v111 row_shr:12 row_mask:0xf bank_mask:0x8
	v_mov_b32_dpp v104, v107 row_shr:12 row_mask:0xf bank_mask:0x8
	v_mov_b32_dpp v100, v103 row_shr:12 row_mask:0xf bank_mask:0x8
	v_mov_b32_dpp v96, v99 row_shr:12 row_mask:0xf bank_mask:0x8
	v_mov_b32_dpp v92, v95 row_shr:12 row_mask:0xf bank_mask:0x8
	v_mov_b32_dpp v88, v91 row_shr:12 row_mask:0xf bank_mask:0x8
	v_mov_b32_dpp v84, v87 row_shr:12 row_mask:0xf bank_mask:0x8
	v_mov_b32_dpp v80, v83 row_shr:12 row_mask:0xf bank_mask:0x8
	v_mov_b32_dpp v76, v79 row_shr:12 row_mask:0xf bank_mask:0x8
	v_mov_b32_dpp v72, v75 row_shr:12 row_mask:0xf bank_mask:0x8
	v_mov_b32_dpp v68, v71 row_shr:12 row_mask:0xf bank_mask:0x8
	v_mov_b32_dpp v64, v67 row_shr:12 row_mask:0xf bank_mask:0x8
	v_mov_b32_dpp v60, v63 row_shr:12 row_mask:0xf bank_mask:0x8
	v_mov_b32_dpp v52, v55 row_shr:12 row_mask:0xf bank_mask:0x8
	v_mov_b32_dpp v48, v51 row_shr:12 row_mask:0xf bank_mask:0x8
	v_mov_b32_dpp v56, v59 row_shr:12 row_mask:0xf bank_mask:0x8
	s_waitcnt lgkmcnt(15)
	v_lshrrev_b32_e32 v152, 10, v136
	v_and_or_b32 v152, v152, s8, v112
	s_waitcnt lgkmcnt(14)
	v_lshrrev_b32_e32 v153, 10, v137
	v_and_or_b32 v153, v153, s8, v112
	s_waitcnt lgkmcnt(13)
	v_lshrrev_b32_e32 v154, 10, v138
	v_and_or_b32 v154, v154, s8, v112
	s_waitcnt lgkmcnt(12)
	v_lshrrev_b32_e32 v155, 10, v139
	v_and_or_b32 v155, v155, s8, v112
	s_waitcnt lgkmcnt(11)
	v_lshrrev_b32_e32 v156, 10, v140
	v_and_or_b32 v156, v156, s8, v112
	s_waitcnt lgkmcnt(10)
	v_lshrrev_b32_e32 v157, 10, v141
	v_and_or_b32 v157, v157, s8, v112
	s_waitcnt lgkmcnt(9)
	v_lshrrev_b32_e32 v158, 10, v142
	v_and_or_b32 v158, v158, s8, v112
	s_waitcnt lgkmcnt(8)
	v_lshrrev_b32_e32 v159, 10, v143
	v_and_or_b32 v159, v159, s8, v112
	s_waitcnt lgkmcnt(7)
	v_lshrrev_b32_e32 v160, 10, v144
	v_and_or_b32 v160, v160, s8, v112
	s_waitcnt lgkmcnt(6)
	v_lshrrev_b32_e32 v161, 10, v145
	v_and_or_b32 v161, v161, s8, v112
	s_waitcnt lgkmcnt(5)
	v_lshrrev_b32_e32 v162, 10, v146
	v_and_or_b32 v162, v162, s8, v112
	s_waitcnt lgkmcnt(4)
	v_lshrrev_b32_e32 v163, 10, v147
	v_and_or_b32 v163, v163, s8, v112
	s_waitcnt lgkmcnt(3)
	v_lshrrev_b32_e32 v164, 10, v148
	v_and_or_b32 v164, v164, s8, v112
	s_waitcnt lgkmcnt(2)
	v_lshrrev_b32_e32 v165, 10, v149
	v_and_or_b32 v165, v165, s8, v112
	s_waitcnt lgkmcnt(1)
	v_lshrrev_b32_e32 v166, 10, v150
	v_and_or_b32 v166, v166, s8, v112
	s_waitcnt lgkmcnt(0)
	v_lshrrev_b32_e32 v167, 10, v151
	v_and_or_b32 v167, v167, s8, v112
	ds_read_b32 v152, v152
	ds_read_b32 v153, v153
	ds_read_b32 v154, v154
	ds_read_b32 v155, v155
	ds_read_b32 v156, v156
	ds_read_b32 v157, v157
	ds_read_b32 v158, v158
	ds_read_b32 v159, v159
	ds_read_b32 v160, v160
	ds_read_b32 v161, v161
	ds_read_b32 v162, v162
	ds_read_b32 v163, v163
	ds_read_b32 v164, v164
	ds_read_b32 v165, v165
	ds_read_b32 v166, v166
	ds_read_b32 v167, v167
	s_waitcnt lgkmcnt(15)
	v_fmac_f32_e32 v152, 0x3e000000, v108
	v_cmp_lt_u32_e64 s[20:21], s45, v136
	s_waitcnt lgkmcnt(14)
	v_fmac_f32_e32 v153, 0x3e000000, v104
	v_cmp_lt_u32_e64 s[8:9], s45, v137
	v_cndmask_b32_e64 v110, v168, v152, s[20:21]
	s_waitcnt lgkmcnt(13)
	v_fmac_f32_e32 v154, 0x3e000000, v100
	v_cmp_lt_u32_e64 s[20:21], s45, v138
	v_cndmask_b32_e64 v109, v168, v153, s[8:9]
	s_waitcnt lgkmcnt(12)
	v_fmac_f32_e32 v155, 0x3e000000, v96
	v_cmp_lt_u32_e64 s[8:9], s45, v139
	v_cndmask_b32_e64 v102, v168, v154, s[20:21]
	s_waitcnt lgkmcnt(11)
	v_fmac_f32_e32 v156, 0x3e000000, v92
	v_cmp_lt_u32_e64 s[20:21], s45, v140
	v_cndmask_b32_e64 v101, v168, v155, s[8:9]
	s_waitcnt lgkmcnt(10)
	v_fmac_f32_e32 v157, 0x3e000000, v88
	v_cmp_lt_u32_e64 s[8:9], s45, v141
	v_cndmask_b32_e64 v94, v168, v156, s[20:21]
	s_waitcnt lgkmcnt(9)
	v_fmac_f32_e32 v158, 0x3e000000, v84
	v_cmp_lt_u32_e64 s[20:21], s45, v142
	v_cndmask_b32_e64 v93, v168, v157, s[8:9]
	s_waitcnt lgkmcnt(8)
	v_fmac_f32_e32 v159, 0x3e000000, v80
	v_cmp_lt_u32_e64 s[8:9], s45, v143
	v_cndmask_b32_e64 v86, v168, v158, s[20:21]
	s_waitcnt lgkmcnt(7)
	v_fmac_f32_e32 v160, 0x3e000000, v76
	v_cmp_lt_u32_e64 s[20:21], s45, v144
	v_cndmask_b32_e64 v85, v168, v159, s[8:9]
	s_waitcnt lgkmcnt(6)
	v_fmac_f32_e32 v161, 0x3e000000, v72
	v_cmp_lt_u32_e64 s[8:9], s45, v145
	v_cndmask_b32_e64 v78, v168, v160, s[20:21]
	s_waitcnt lgkmcnt(5)
	v_fmac_f32_e32 v162, 0x3e000000, v68
	v_cmp_lt_u32_e64 s[20:21], s45, v146
	v_cndmask_b32_e64 v77, v168, v161, s[8:9]
	s_waitcnt lgkmcnt(4)
	v_fmac_f32_e32 v163, 0x3e000000, v64
	v_cmp_lt_u32_e64 s[8:9], s45, v147
	v_cndmask_b32_e64 v70, v168, v162, s[20:21]
	s_waitcnt lgkmcnt(3)
	v_fmac_f32_e32 v164, 0x3e000000, v60
	v_cmp_lt_u32_e64 s[20:21], s45, v148
	v_cndmask_b32_e64 v69, v168, v163, s[8:9]
	s_waitcnt lgkmcnt(2)
	v_fmac_f32_e32 v165, 0x3e000000, v52
	v_cmp_lt_u32_e64 s[8:9], s45, v149
	v_cndmask_b32_e64 v62, v168, v164, s[20:21]
	s_waitcnt lgkmcnt(1)
	v_fmac_f32_e32 v166, 0x3e000000, v48
	v_cmp_lt_u32_e64 s[20:21], s45, v150
	v_cndmask_b32_e64 v61, v168, v165, s[8:9]
	s_waitcnt lgkmcnt(0)
	v_fmac_f32_e32 v167, 0x3e000000, v56
	v_cmp_lt_u32_e64 s[8:9], s45, v151
	v_cndmask_b32_e64 v50, v168, v166, s[20:21]
	s_nop 1
	v_cndmask_b32_e64 v49, v168, v167, s[8:9]
	v_max3_f32 v48, v110, s46, v109
	v_max3_f32 v48, v48, v102, v101
	v_max3_f32 v48, v48, v94, v93
	v_max3_f32 v48, v48, v86, v85
	v_max3_f32 v48, v48, v78, v77
	v_max3_f32 v48, v48, v70, v69
	v_max3_f32 v48, v48, v62, v61
	v_max3_f32 v48, v48, v50, v49
	v_mov_b32_e32 v51, v113
	v_mov_b32_e32 v68, v113
	v_bfe_u32 v98, v120, 4, 2
	v_mov_b32_dpp v51, v48 row_ror:4 row_mask:0xf bank_mask:0xf
	v_max_f32_e32 v51, v51, v51
	v_max_f32_e32 v48, v48, v51
	v_mov_b32_e32 v51, v113
	v_lshrrev_b32_e32 v100, 2, v116
	v_lshl_or_b32 v98, v98, 2, v100
	v_mov_b32_dpp v51, v48 row_ror:8 row_mask:0xf bank_mask:0xf
	v_max_f32_e32 v51, v51, v51
	v_max_f32_e32 v48, v48, v51
	v_mov_b32_e32 v51, v48
	s_nop 1
	v_permlane16_swap_b32_e32 v48, v51
	v_max_f32_e32 v51, v51, v51
	v_max_f32_e32 v48, v48, v48
	v_max_f32_e32 v48, v48, v51
	v_mov_b32_e32 v51, v48
	s_nop 1
	v_permlane32_swap_b32_e32 v48, v51
	v_max_f32_e32 v51, v51, v51
	v_max_f32_e32 v48, v48, v48
	v_max_f32_e32 v48, v48, v51
	v_sub_f32_e32 v51, v110, v48
	v_mul_f32_e32 v51, 0x3fb8aa3b, v51
	v_sub_f32_e32 v52, v109, v48
	v_exp_f32_e32 v51, v51
	v_mul_f32_e32 v52, 0x3fb8aa3b, v52
	v_sub_f32_e32 v53, v102, v48
	v_exp_f32_e32 v52, v52
	v_mul_f32_e32 v53, 0x3fb8aa3b, v53
	v_sub_f32_e32 v54, v101, v48
	v_exp_f32_e32 v53, v53
	v_mul_f32_e32 v54, 0x3fb8aa3b, v54
	v_sub_f32_e32 v56, v94, v48
	v_exp_f32_e32 v54, v54
	v_mul_f32_e32 v56, 0x3fb8aa3b, v56
	v_sub_f32_e32 v57, v93, v48
	v_add_f32_e32 v55, 0, v51
	v_exp_f32_e32 v56, v56
	v_mul_f32_e32 v57, 0x3fb8aa3b, v57
	v_sub_f32_e32 v58, v86, v48
	v_add_f32_e32 v55, v52, v55
	v_exp_f32_e32 v57, v57
	v_mul_f32_e32 v58, 0x3fb8aa3b, v58
	v_sub_f32_e32 v59, v85, v48
	v_add_f32_e32 v55, v53, v55
	v_exp_f32_e32 v58, v58
	v_mul_f32_e32 v59, 0x3fb8aa3b, v59
	v_sub_f32_e32 v60, v78, v48
	v_add_f32_e32 v55, v54, v55
	v_exp_f32_e32 v59, v59
	v_mul_f32_e32 v60, 0x3fb8aa3b, v60
	v_sub_f32_e32 v63, v77, v48
	v_sub_f32_e32 v64, v70, v48
	v_add_f32_e32 v55, v56, v55
	v_exp_f32_e32 v60, v60
	v_mul_f32_e32 v63, 0x3fb8aa3b, v63
	v_mul_f32_e32 v64, 0x3fb8aa3b, v64
	v_add_f32_e32 v55, v57, v55
	v_exp_f32_e32 v63, v63
	v_exp_f32_e32 v101, v64
	v_sub_f32_e32 v64, v69, v48
	v_add_f32_e32 v55, v58, v55
	v_mul_f32_e32 v64, 0x3fb8aa3b, v64
	v_sub_f32_e32 v62, v62, v48
	v_add_f32_e32 v55, v59, v55
	v_exp_f32_e32 v102, v64
	v_mul_f32_e32 v62, 0x3fb8aa3b, v62
	v_sub_f32_e32 v61, v61, v48
	v_add_f32_e32 v55, v60, v55
	v_exp_f32_e32 v103, v62
	v_mul_f32_e32 v61, 0x3fb8aa3b, v61
	v_sub_f32_e32 v50, v50, v48
	v_add_f32_e32 v55, v63, v55
	v_exp_f32_e32 v104, v61
	v_mul_f32_e32 v50, 0x3fb8aa3b, v50
	v_sub_f32_e32 v48, v49, v48
	v_add_f32_e32 v55, v101, v55
	v_exp_f32_e32 v105, v50
	v_mul_f32_e32 v48, 0x3fb8aa3b, v48
	v_add_f32_e32 v55, v102, v55
	v_exp_f32_e32 v106, v48
	v_add_f32_e32 v48, v103, v55
	v_add_f32_e32 v48, v104, v48
	v_add_f32_e32 v48, v105, v48
	v_add_f32_e32 v48, v106, v48
	v_mov_b32_e32 v50, v113
	v_mov_b32_e32 v55, v113
	v_add_f32_dpp v48, v48, v48 row_ror:4 row_mask:0xf bank_mask:0xf bound_ctrl:1
	v_mov_b32_e32 v61, v113
	v_mov_b32_dpp v50, v51 row_shl:8 row_mask:0xf bank_mask:0x1 bound_ctrl:1
	v_add_f32_dpp v48, v48, v48 row_ror:8 row_mask:0xf bank_mask:0xf bound_ctrl:1
	v_mov_b32_e32 v49, v48
	s_nop 1
	v_permlane16_swap_b32_e32 v48, v49
	v_add_f32_e32 v96, v48, v49
	v_mov_b32_e32 v49, v113
	v_cndmask_b32_e32 v48, 0, v51, vcc
	v_mov_b32_dpp v55, v51 row_shl:12 row_mask:0xf bank_mask:0x1 bound_ctrl:1
	v_mov_b32_dpp v49, v51 row_shl:4 row_mask:0xf bank_mask:0x1 bound_ctrl:1
	v_cndmask_b32_e32 v51, 0, v52, vcc
	v_mov_b32_dpp v61, v52 row_shl:4 row_mask:0xf bank_mask:0x1 bound_ctrl:1
	v_mov_b32_e32 v62, v113
	v_mov_b32_e32 v64, v113
	v_cvt_pk_bf16_f32 v76, v48, v49
	v_cvt_pk_bf16_f32 v77, v50, v55
	v_cvt_pk_bf16_f32 v78, v51, v61
	v_mov_b32_e32 v49, v113
	v_mov_b32_e32 v50, v113
	v_mov_b32_e32 v51, v113
	v_mov_b32_dpp v62, v52 row_shl:8 row_mask:0xf bank_mask:0x1 bound_ctrl:1
	v_mov_b32_dpp v64, v52 row_shl:12 row_mask:0xf bank_mask:0x1 bound_ctrl:1
	v_cndmask_b32_e32 v48, 0, v53, vcc
	v_mov_b32_dpp v49, v53 row_shl:4 row_mask:0xf bank_mask:0x1 bound_ctrl:1
	v_mov_b32_dpp v50, v53 row_shl:8 row_mask:0xf bank_mask:0x1 bound_ctrl:1
	v_mov_b32_dpp v51, v53 row_shl:12 row_mask:0xf bank_mask:0x1 bound_ctrl:1
	v_cvt_pk_bf16_f32 v79, v62, v64
	v_mov_b32_e32 v53, v113
	v_cvt_pk_bf16_f32 v64, v48, v49
	v_cvt_pk_bf16_f32 v65, v50, v51
	v_mov_b32_e32 v49, v113
	v_mov_b32_e32 v50, v113
	v_mov_b32_e32 v51, v113
	v_cndmask_b32_e32 v52, 0, v54, vcc
	v_mov_b32_dpp v53, v54 row_shl:4 row_mask:0xf bank_mask:0x1 bound_ctrl:1
	v_cndmask_b32_e32 v48, 0, v56, vcc
	v_mov_b32_dpp v49, v56 row_shl:4 row_mask:0xf bank_mask:0x1 bound_ctrl:1
	v_mov_b32_dpp v50, v56 row_shl:8 row_mask:0xf bank_mask:0x1 bound_ctrl:1
	v_mov_b32_dpp v51, v56 row_shl:12 row_mask:0xf bank_mask:0x1 bound_ctrl:1
	v_cvt_pk_bf16_f32 v66, v52, v53
	v_cvt_pk_bf16_f32 v52, v48, v49
	v_cvt_pk_bf16_f32 v53, v50, v51
	v_mov_b32_e32 v51, v113
	v_cndmask_b32_e32 v50, 0, v58, vcc
	v_mov_b32_dpp v51, v58 row_shl:4 row_mask:0xf bank_mask:0x1 bound_ctrl:1
	v_cvt_pk_bf16_f32 v72, v50, v51
	global_load_dwordx4 v[80:83], v220, s[18:19]
	global_load_dwordx4 v[84:87], v221, s[18:19]
	global_load_dwordx4 v[88:91], v222, s[18:19]
	global_load_dwordx4 v[92:95], v223, s[18:19]
	v_mov_b32_e32 v55, v113
	v_mov_b32_e32 v61, v113
	v_mov_b32_e32 v56, v113
	v_mov_b32_dpp v55, v54 row_shl:8 row_mask:0xf bank_mask:0x1 bound_ctrl:1
	v_mov_b32_dpp v61, v54 row_shl:12 row_mask:0xf bank_mask:0x1 bound_ctrl:1
	v_cvt_pk_bf16_f32 v67, v55, v61
	v_mov_b32_e32 v55, v113
	v_mov_b32_e32 v61, v113
	v_cndmask_b32_e32 v54, 0, v57, vcc
	v_mov_b32_dpp v55, v57 row_shl:4 row_mask:0xf bank_mask:0x1 bound_ctrl:1
	v_mov_b32_dpp v56, v57 row_shl:8 row_mask:0xf bank_mask:0x1 bound_ctrl:1
	v_mov_b32_dpp v61, v57 row_shl:12 row_mask:0xf bank_mask:0x1 bound_ctrl:1
	v_cvt_pk_bf16_f32 v54, v54, v55
	v_cvt_pk_bf16_f32 v55, v56, v61
	v_mov_b32_e32 v56, v113
	v_mov_b32_e32 v57, v113
	v_mov_b32_e32 v61, v113
	v_mov_b32_dpp v56, v58 row_shl:8 row_mask:0xf bank_mask:0x1 bound_ctrl:1
	v_mov_b32_dpp v57, v58 row_shl:12 row_mask:0xf bank_mask:0x1 bound_ctrl:1
	v_cndmask_b32_e32 v58, 0, v59, vcc
	v_mov_b32_dpp v61, v59 row_shl:4 row_mask:0xf bank_mask:0x1 bound_ctrl:1
	v_mov_b32_e32 v62, v113
	v_mov_b32_dpp v68, v59 row_shl:12 row_mask:0xf bank_mask:0x1 bound_ctrl:1
	v_cvt_pk_bf16_f32 v74, v58, v61
	v_mov_b32_dpp v62, v59 row_shl:8 row_mask:0xf bank_mask:0x1 bound_ctrl:1
	v_mov_b32_e32 v49, v113
	v_mov_b32_e32 v50, v113
	v_mov_b32_e32 v51, v113
	v_mov_b32_e32 v58, v113
	v_mov_b32_e32 v59, v113
	v_cvt_pk_bf16_f32 v73, v56, v57
	v_cndmask_b32_e32 v48, 0, v60, vcc
	v_mov_b32_dpp v49, v60 row_shl:4 row_mask:0xf bank_mask:0x1 bound_ctrl:1
	v_mov_b32_dpp v50, v60 row_shl:8 row_mask:0xf bank_mask:0x1 bound_ctrl:1
	v_mov_b32_dpp v51, v60 row_shl:12 row_mask:0xf bank_mask:0x1 bound_ctrl:1
	v_mov_b32_e32 v57, v113
	v_mov_b32_dpp v58, v63 row_shl:8 row_mask:0xf bank_mask:0x1 bound_ctrl:1
	v_mov_b32_dpp v59, v63 row_shl:12 row_mask:0xf bank_mask:0x1 bound_ctrl:1
	v_cvt_pk_bf16_f32 v75, v62, v68
	v_cndmask_b32_e32 v56, 0, v63, vcc
	v_mov_b32_dpp v57, v63 row_shl:4 row_mask:0xf bank_mask:0x1 bound_ctrl:1
	v_cvt_pk_bf16_f32 v68, v48, v49
	v_cvt_pk_bf16_f32 v69, v50, v51
	v_cvt_pk_bf16_f32 v71, v58, v59
	v_mov_b32_e32 v49, v113
	v_mov_b32_e32 v50, v113
	v_mov_b32_e32 v51, v113
	v_mov_b32_e32 v58, v113
	v_mov_b32_e32 v59, v113
	v_cvt_pk_bf16_f32 v70, v56, v57
	v_cndmask_b32_e32 v48, 0, v101, vcc
	v_mov_b32_dpp v49, v101 row_shl:4 row_mask:0xf bank_mask:0x1 bound_ctrl:1
	v_mov_b32_dpp v50, v101 row_shl:8 row_mask:0xf bank_mask:0x1 bound_ctrl:1
	v_mov_b32_dpp v51, v101 row_shl:12 row_mask:0xf bank_mask:0x1 bound_ctrl:1
	v_mov_b32_e32 v57, v113
	v_mov_b32_dpp v58, v102 row_shl:8 row_mask:0xf bank_mask:0x1 bound_ctrl:1
	v_mov_b32_dpp v59, v102 row_shl:12 row_mask:0xf bank_mask:0x1 bound_ctrl:1
	v_cndmask_b32_e32 v56, 0, v102, vcc
	v_mov_b32_dpp v57, v102 row_shl:4 row_mask:0xf bank_mask:0x1 bound_ctrl:1
	v_cvt_pk_bf16_f32 v60, v48, v49
	v_cvt_pk_bf16_f32 v61, v50, v51
	v_cvt_pk_bf16_f32 v63, v58, v59
	v_mov_b32_e32 v49, v113
	v_mov_b32_e32 v50, v113
	v_mov_b32_e32 v51, v113
	v_mov_b32_e32 v59, v113
	v_mov_b32_e32 v101, v113
	v_mov_b32_e32 v102, v113
	v_cndmask_b32_e32 v48, 0, v103, vcc
	v_mov_b32_dpp v49, v103 row_shl:4 row_mask:0xf bank_mask:0x1 bound_ctrl:1
	v_mov_b32_dpp v50, v103 row_shl:8 row_mask:0xf bank_mask:0x1 bound_ctrl:1
	v_mov_b32_dpp v51, v103 row_shl:12 row_mask:0xf bank_mask:0x1 bound_ctrl:1
	v_cndmask_b32_e32 v58, 0, v104, vcc
	v_mov_b32_dpp v59, v104 row_shl:4 row_mask:0xf bank_mask:0x1 bound_ctrl:1
	v_mov_b32_dpp v101, v104 row_shl:8 row_mask:0xf bank_mask:0x1 bound_ctrl:1
	v_mov_b32_dpp v102, v104 row_shl:12 row_mask:0xf bank_mask:0x1 bound_ctrl:1
	v_cvt_pk_bf16_f32 v62, v56, v57
	v_cvt_pk_bf16_f32 v56, v48, v49
	v_cvt_pk_bf16_f32 v57, v50, v51
	v_cvt_pk_bf16_f32 v58, v58, v59
	v_cvt_pk_bf16_f32 v59, v101, v102
	v_mov_b32_e32 v49, v113
	v_mov_b32_e32 v50, v113
	v_mov_b32_e32 v51, v113
	v_mov_b32_e32 v102, v113
	v_mov_b32_e32 v103, v113
	v_mov_b32_e32 v104, v113
	v_lshlrev_b32_e32 v100, 3, v120
	v_mov_b32_e32 v97, v96
	v_cndmask_b32_e32 v48, 0, v105, vcc
	v_mov_b32_dpp v49, v105 row_shl:4 row_mask:0xf bank_mask:0x1 bound_ctrl:1
	v_mov_b32_dpp v50, v105 row_shl:8 row_mask:0xf bank_mask:0x1 bound_ctrl:1
	v_mov_b32_dpp v51, v105 row_shl:12 row_mask:0xf bank_mask:0x1 bound_ctrl:1
	v_cndmask_b32_e32 v101, 0, v106, vcc
	v_mov_b32_dpp v102, v106 row_shl:4 row_mask:0xf bank_mask:0x1 bound_ctrl:1
	v_mov_b32_dpp v103, v106 row_shl:8 row_mask:0xf bank_mask:0x1 bound_ctrl:1
	v_mov_b32_dpp v104, v106 row_shl:12 row_mask:0xf bank_mask:0x1 bound_ctrl:1
	v_mul_u32_u24_e32 v98, 0xa0, v98
	v_and_b32_e32 v100, 24, v100
	v_mul_u32_u24_e32 v99, 0xa0, v122
	v_permlane32_swap_b32_e32 v96, v97
	v_cvt_pk_bf16_f32 v48, v48, v49
	v_cvt_pk_bf16_f32 v49, v50, v51
	v_cvt_pk_bf16_f32 v50, v101, v102
	v_cvt_pk_bf16_f32 v51, v103, v104
	v_add3_u32 v110, s47, v98, v100
	v_add_u32_e32 v111, v121, v99
	s_waitcnt vmcnt(15)
	ds_write_b128 v111, v[32:35] offset:1024
	s_waitcnt vmcnt(14)
	ds_write_b128 v111, v[36:39] offset:2304
	s_waitcnt vmcnt(13)
	ds_write_b128 v111, v[40:43] offset:3584
	s_waitcnt vmcnt(12)
	ds_write_b128 v111, v[44:47] offset:4864
	ds_read_b64_tr_b16 v[34:35], v110 offset:3584
	ds_read_b64_tr_b16 v[32:33], v110 offset:1024
	ds_read_b64_tr_b16 v[36:37], v110 offset:1056
	ds_read_b64_tr_b16 v[40:41], v110 offset:1088
	ds_read_b64_tr_b16 v[44:45], v110 offset:1120
	ds_read_b64_tr_b16 v[38:39], v110 offset:3616
	ds_read_b64_tr_b16 v[42:43], v110 offset:3648
	ds_read_b64_tr_b16 v[46:47], v110 offset:3680
	s_waitcnt lgkmcnt(6)
	v_mfma_f32_16x16x32_bf16 v[32:35], v[76:79], v[32:35], 0
	s_waitcnt lgkmcnt(0)
	global_load_dwordx4 v[98:101], v224, s[18:19]
	global_load_dwordx4 v[102:105], v225, s[18:19]
	global_load_dwordx4 v[106:109], v226, s[18:19]
	global_load_dwordx4 v[120:123], v227, s[18:19]
	v_mfma_f32_16x16x32_bf16 v[36:39], v[76:79], v[36:39], 0
	v_mfma_f32_16x16x32_bf16 v[40:43], v[76:79], v[40:43], 0
	v_mfma_f32_16x16x32_bf16 v[44:47], v[76:79], v[44:47], 0
	s_waitcnt vmcnt(15)
	ds_write_b128 v111, v[16:19] offset:1024
	s_waitcnt vmcnt(14)
	ds_write_b128 v111, v[20:23] offset:2304
	s_waitcnt vmcnt(13)
	ds_write_b128 v111, v[24:27] offset:3584
	s_waitcnt vmcnt(12)
	ds_write_b128 v111, v[28:31] offset:4864
	ds_read_b64_tr_b16 v[18:19], v110 offset:3584
	ds_read_b64_tr_b16 v[16:17], v110 offset:1024
	ds_read_b64_tr_b16 v[20:21], v110 offset:1056
	ds_read_b64_tr_b16 v[24:25], v110 offset:1088
	ds_read_b64_tr_b16 v[28:29], v110 offset:1120
	ds_read_b64_tr_b16 v[22:23], v110 offset:3616
	ds_read_b64_tr_b16 v[26:27], v110 offset:3648
	ds_read_b64_tr_b16 v[30:31], v110 offset:3680
	s_waitcnt lgkmcnt(6)
	v_mfma_f32_16x16x32_bf16 v[16:19], v[64:67], v[16:19], v[32:35]
	s_waitcnt lgkmcnt(1)
	v_mfma_f32_16x16x32_bf16 v[24:27], v[64:67], v[24:27], v[40:43]
	s_nop 0
	s_waitcnt lgkmcnt(0)
	v_mfma_f32_16x16x32_bf16 v[20:23], v[64:67], v[20:23], v[36:39]
	global_load_dwordx4 v[32:35], v228, s[18:19]
	s_nop 0
	global_load_dwordx4 v[36:39], v229, s[18:19]
	global_load_dwordx4 v[40:43], v230, s[18:19]
	global_load_dwordx4 v[76:79], v231, s[18:19]
	v_mfma_f32_16x16x32_bf16 v[28:31], v[64:67], v[28:31], v[44:47]
	s_waitcnt vmcnt(15)
	ds_write_b128 v111, v[0:3] offset:1024
	s_waitcnt vmcnt(14)
	ds_write_b128 v111, v[4:7] offset:2304
	s_waitcnt vmcnt(13)
	ds_write_b128 v111, v[8:11] offset:3584
	s_waitcnt vmcnt(12)
	ds_write_b128 v111, v[12:15] offset:4864
	ds_read_b64_tr_b16 v[2:3], v110 offset:3584
	ds_read_b64_tr_b16 v[0:1], v110 offset:1024
	ds_read_b64_tr_b16 v[4:5], v110 offset:1056
	ds_read_b64_tr_b16 v[8:9], v110 offset:1088
	ds_read_b64_tr_b16 v[12:13], v110 offset:1120
	ds_read_b64_tr_b16 v[6:7], v110 offset:3616
	ds_read_b64_tr_b16 v[10:11], v110 offset:3648
	ds_read_b64_tr_b16 v[14:15], v110 offset:3680
	s_waitcnt lgkmcnt(6)
	v_mfma_f32_16x16x32_bf16 v[0:3], v[52:55], v[0:3], v[16:19]
	s_waitcnt lgkmcnt(1)
	v_mfma_f32_16x16x32_bf16 v[8:11], v[52:55], v[8:11], v[24:27]
	s_nop 0
	s_waitcnt lgkmcnt(0)
	v_mfma_f32_16x16x32_bf16 v[4:7], v[52:55], v[4:7], v[20:23]
	global_load_dwordx4 v[16:19], v232, s[18:19]
	s_nop 0
	global_load_dwordx4 v[20:23], v233, s[18:19]
	global_load_dwordx4 v[24:27], v234, s[18:19]
	global_load_dwordx4 v[44:47], v235, s[18:19]
	v_mfma_f32_16x16x32_bf16 v[12:15], v[52:55], v[12:15], v[28:31]
	s_waitcnt vmcnt(15)
	ds_write_b128 v111, v[80:83] offset:1024
	s_waitcnt vmcnt(14)
	ds_write_b128 v111, v[84:87] offset:2304
	s_waitcnt vmcnt(13)
	ds_write_b128 v111, v[88:91] offset:3584
	s_waitcnt vmcnt(12)
	ds_write_b128 v111, v[92:95] offset:4864
	ds_read_b64_tr_b16 v[30:31], v110 offset:3584
	ds_read_b64_tr_b16 v[28:29], v110 offset:1024
	ds_read_b64_tr_b16 v[52:53], v110 offset:1056
	ds_read_b64_tr_b16 v[64:65], v110 offset:1088
	ds_read_b64_tr_b16 v[80:81], v110 offset:1120
	ds_read_b64_tr_b16 v[54:55], v110 offset:3616
	ds_read_b64_tr_b16 v[66:67], v110 offset:3648
	ds_read_b64_tr_b16 v[82:83], v110 offset:3680
	s_waitcnt lgkmcnt(6)
	v_mfma_f32_16x16x32_bf16 v[0:3], v[72:75], v[28:31], v[0:3]
	s_waitcnt lgkmcnt(0)
	v_mfma_f32_16x16x32_bf16 v[8:11], v[72:75], v[64:67], v[8:11]
	v_mfma_f32_16x16x32_bf16 v[4:7], v[72:75], v[52:55], v[4:7]
	global_load_dwordx4 v[28:31], v236, s[18:19]
	global_load_dwordx4 v[52:55], v237, s[18:19]
	global_load_dwordx4 v[64:67], v238, s[18:19]
	global_load_dwordx4 v[84:87], v239, s[18:19]
	v_lshl_add_u32 v134, v117, 4, s47
	ds_write_b128 v134, v[204:207]
	ds_read2_b32 v[136:137], v119 offset1:8
	ds_read2_b32 v[138:139], v119 offset0:16 offset1:24
	ds_read2_b32 v[140:141], v119 offset0:32 offset1:40
	ds_read2_b32 v[142:143], v119 offset0:48 offset1:56
	ds_read2_b32 v[144:145], v119 offset0:64 offset1:72
	ds_read2_b32 v[146:147], v119 offset0:80 offset1:88
	ds_read2_b32 v[148:149], v119 offset0:96 offset1:104
	ds_read2_b32 v[150:151], v119 offset0:112 offset1:120
	ds_read2_b32 v[152:153], v119 offset0:128 offset1:136
	ds_read2_b32 v[154:155], v119 offset0:144 offset1:152
	ds_read2_b32 v[156:157], v119 offset0:160 offset1:168
	ds_read2_b32 v[158:159], v119 offset0:176 offset1:184
	ds_read2_b32 v[160:161], v119 offset0:192 offset1:200
	ds_read2_b32 v[162:163], v119 offset0:208 offset1:216
	ds_read2_b32 v[164:165], v119 offset0:224 offset1:232
	ds_read2_b32 v[166:167], v119 offset0:240 offset1:248
	v_mfma_f32_16x16x32_bf16 v[12:15], v[72:75], v[80:83], v[12:15]
	s_waitcnt vmcnt(15)
	ds_write_b128 v111, v[98:101] offset:1024
	s_waitcnt vmcnt(14)
	ds_write_b128 v111, v[102:105] offset:2304
	s_waitcnt vmcnt(13)
	ds_write_b128 v111, v[106:109] offset:3584
	s_waitcnt vmcnt(12)
	ds_write_b128 v111, v[120:123] offset:4864
	ds_read_b64_tr_b16 v[74:75], v110 offset:3584
	ds_read_b64_tr_b16 v[72:73], v110 offset:1024
	ds_read_b64_tr_b16 v[80:81], v110 offset:1056
	ds_read_b64_tr_b16 v[88:89], v110 offset:1088
	ds_read_b64_tr_b16 v[92:93], v110 offset:1120
	ds_read_b64_tr_b16 v[82:83], v110 offset:3616
	ds_read_b64_tr_b16 v[90:91], v110 offset:3648
	ds_read_b64_tr_b16 v[94:95], v110 offset:3680
	s_waitcnt lgkmcnt(6)
	v_mfma_f32_16x16x32_bf16 v[0:3], v[68:71], v[72:75], v[0:3]
	s_waitcnt lgkmcnt(2)
	v_mfma_f32_16x16x32_bf16 v[4:7], v[68:71], v[80:83], v[4:7]
	s_waitcnt lgkmcnt(1)
	v_mfma_f32_16x16x32_bf16 v[8:11], v[68:71], v[88:91], v[8:11]
	s_waitcnt lgkmcnt(0)
	v_mfma_f32_16x16x32_bf16 v[12:15], v[68:71], v[92:95], v[12:15]
	s_waitcnt vmcnt(11)
	ds_write_b128 v111, v[32:35] offset:1024
	s_waitcnt vmcnt(10)
	ds_write_b128 v111, v[36:39] offset:2304
	s_waitcnt vmcnt(9)
	ds_write_b128 v111, v[40:43] offset:3584
	s_waitcnt vmcnt(8)
	ds_write_b128 v111, v[76:79] offset:4864
	ds_read_b64_tr_b16 v[34:35], v110 offset:3584
	ds_read_b64_tr_b16 v[32:33], v110 offset:1024
	ds_read_b64_tr_b16 v[36:37], v110 offset:1056
	ds_read_b64_tr_b16 v[40:41], v110 offset:1088
	ds_read_b64_tr_b16 v[68:69], v110 offset:1120
	ds_read_b64_tr_b16 v[38:39], v110 offset:3616
	ds_read_b64_tr_b16 v[42:43], v110 offset:3648
	ds_read_b64_tr_b16 v[70:71], v110 offset:3680
	s_waitcnt lgkmcnt(6)
	v_mfma_f32_16x16x32_bf16 v[0:3], v[60:63], v[32:35], v[0:3]
	s_waitcnt lgkmcnt(2)
	v_mfma_f32_16x16x32_bf16 v[4:7], v[60:63], v[36:39], v[4:7]
	s_waitcnt lgkmcnt(1)
	v_mfma_f32_16x16x32_bf16 v[8:11], v[60:63], v[40:43], v[8:11]
	s_waitcnt lgkmcnt(0)
	v_mfma_f32_16x16x32_bf16 v[12:15], v[60:63], v[68:71], v[12:15]
	v_lshlrev_b32_e32 v136, 9, v136
	v_lshlrev_b32_e32 v137, 9, v137
	v_and_or_b32 v208, v136, s43, v118
	v_and_or_b32 v209, v137, s43, v118
	v_lshlrev_b32_e32 v138, 9, v138
	v_lshlrev_b32_e32 v139, 9, v139
	v_and_or_b32 v210, v138, s43, v118
	v_and_or_b32 v211, v139, s43, v118
	v_lshlrev_b32_e32 v140, 9, v140
	v_lshlrev_b32_e32 v141, 9, v141
	v_and_or_b32 v212, v140, s43, v118
	v_and_or_b32 v213, v141, s43, v118
	v_lshlrev_b32_e32 v142, 9, v142
	v_lshlrev_b32_e32 v143, 9, v143
	v_and_or_b32 v214, v142, s43, v118
	v_and_or_b32 v215, v143, s43, v118
	v_lshlrev_b32_e32 v144, 9, v144
	v_lshlrev_b32_e32 v145, 9, v145
	v_and_or_b32 v216, v144, s43, v118
	v_and_or_b32 v217, v145, s43, v118
	v_lshlrev_b32_e32 v146, 9, v146
	v_lshlrev_b32_e32 v147, 9, v147
	v_and_or_b32 v218, v146, s43, v118
	v_and_or_b32 v219, v147, s43, v118
	v_lshlrev_b32_e32 v148, 9, v148
	v_lshlrev_b32_e32 v149, 9, v149
	v_and_or_b32 v220, v148, s43, v118
	v_and_or_b32 v221, v149, s43, v118
	v_lshlrev_b32_e32 v150, 9, v150
	v_lshlrev_b32_e32 v151, 9, v151
	v_and_or_b32 v222, v150, s43, v118
	v_and_or_b32 v223, v151, s43, v118
	v_lshlrev_b32_e32 v152, 9, v152
	v_lshlrev_b32_e32 v153, 9, v153
	v_and_or_b32 v224, v152, s43, v118
	v_and_or_b32 v225, v153, s43, v118
	v_lshlrev_b32_e32 v154, 9, v154
	v_lshlrev_b32_e32 v155, 9, v155
	v_and_or_b32 v226, v154, s43, v118
	v_and_or_b32 v227, v155, s43, v118
	v_lshlrev_b32_e32 v156, 9, v156
	v_lshlrev_b32_e32 v157, 9, v157
	v_and_or_b32 v228, v156, s43, v118
	v_and_or_b32 v229, v157, s43, v118
	v_lshlrev_b32_e32 v158, 9, v158
	v_lshlrev_b32_e32 v159, 9, v159
	v_and_or_b32 v230, v158, s43, v118
	v_and_or_b32 v231, v159, s43, v118
	v_lshlrev_b32_e32 v160, 9, v160
	v_lshlrev_b32_e32 v161, 9, v161
	v_and_or_b32 v232, v160, s43, v118
	v_and_or_b32 v233, v161, s43, v118
	v_lshlrev_b32_e32 v162, 9, v162
	v_lshlrev_b32_e32 v163, 9, v163
	v_and_or_b32 v234, v162, s43, v118
	v_and_or_b32 v235, v163, s43, v118
	v_lshlrev_b32_e32 v164, 9, v164
	v_lshlrev_b32_e32 v165, 9, v165
	v_and_or_b32 v236, v164, s43, v118
	v_and_or_b32 v237, v165, s43, v118
	v_lshlrev_b32_e32 v166, 9, v166
	v_lshlrev_b32_e32 v167, 9, v167
	v_and_or_b32 v238, v166, s43, v118
	v_and_or_b32 v239, v167, s43, v118
	s_waitcnt vmcnt(7)
	ds_write_b128 v111, v[16:19] offset:1024
	s_waitcnt vmcnt(6)
	ds_write_b128 v111, v[20:23] offset:2304
	s_waitcnt vmcnt(5)
	ds_write_b128 v111, v[24:27] offset:3584
	s_waitcnt vmcnt(4)
	ds_write_b128 v111, v[44:47] offset:4864
	ds_read_b64_tr_b16 v[18:19], v110 offset:3584
	ds_read_b64_tr_b16 v[16:17], v110 offset:1024
	ds_read_b64_tr_b16 v[20:21], v110 offset:1056
	ds_read_b64_tr_b16 v[24:25], v110 offset:1088
	ds_read_b64_tr_b16 v[32:33], v110 offset:1120
	ds_read_b64_tr_b16 v[22:23], v110 offset:3616
	ds_read_b64_tr_b16 v[26:27], v110 offset:3648
	ds_read_b64_tr_b16 v[34:35], v110 offset:3680
	s_waitcnt lgkmcnt(6)
	v_mfma_f32_16x16x32_bf16 v[0:3], v[56:59], v[16:19], v[0:3]
	s_waitcnt lgkmcnt(2)
	v_mfma_f32_16x16x32_bf16 v[4:7], v[56:59], v[20:23], v[4:7]
	s_waitcnt lgkmcnt(1)
	v_mfma_f32_16x16x32_bf16 v[8:11], v[56:59], v[24:27], v[8:11]
	s_waitcnt lgkmcnt(0)
	v_mfma_f32_16x16x32_bf16 v[16:19], v[56:59], v[32:35], v[12:15]
	s_waitcnt vmcnt(3)
	ds_write_b128 v111, v[28:31] offset:1024
	s_waitcnt vmcnt(2)
	ds_write_b128 v111, v[52:55] offset:2304
	s_waitcnt vmcnt(1)
	ds_write_b128 v111, v[64:67] offset:3584
	s_waitcnt vmcnt(0)
	ds_write_b128 v111, v[84:87] offset:4864
	ds_read_b64_tr_b16 v[14:15], v110 offset:3584
	ds_read_b64_tr_b16 v[12:13], v110 offset:1024
	ds_read_b64_tr_b16 v[20:21], v110 offset:1056
	ds_read_b64_tr_b16 v[24:25], v110 offset:1088
	ds_read_b64_tr_b16 v[28:29], v110 offset:1120
	ds_read_b64_tr_b16 v[22:23], v110 offset:3616
	ds_read_b64_tr_b16 v[26:27], v110 offset:3648
	ds_read_b64_tr_b16 v[30:31], v110 offset:3680
	s_waitcnt lgkmcnt(6)
	v_mfma_f32_16x16x32_bf16 v[12:15], v[48:51], v[12:15], v[0:3]
	v_cmp_gt_u32_e32 vcc, 16, v117
	s_waitcnt lgkmcnt(1)
	v_mfma_f32_16x16x32_bf16 v[0:3], v[48:51], v[24:27], v[8:11]
	s_waitcnt lgkmcnt(0)
	v_mfma_f32_16x16x32_bf16 v[8:11], v[48:51], v[28:31], v[16:19]
	s_nop 2
	v_add_f32_e32 v19, v96, v97
	ds_bpermute_b32 v16, v114, v19
	ds_bpermute_b32 v17, v114, v19 offset:4
	ds_bpermute_b32 v18, v114, v19 offset:8
	ds_bpermute_b32 v19, v114, v19 offset:12
	v_mfma_f32_16x16x32_bf16 v[4:7], v[48:51], v[20:23], v[4:7]
	s_and_saveexec_b64 s[8:9], vcc
	s_cbranch_execz .LBB0_1251
	s_waitcnt lgkmcnt(0)
	v_div_scale_f32 v20, s[18:19], v19, v19, 1.0
	v_rcp_f32_e32 v21, v20
	v_div_scale_f32 v22, vcc, 1.0, v19, 1.0
	v_lshlrev_b32_e32 v112, 1, v116
	v_fma_f32 v23, -v20, v21, 1.0
	v_fmac_f32_e32 v21, v23, v21
	v_mul_f32_e32 v23, v22, v21
	v_fma_f32 v24, -v20, v23, v22
	v_fmac_f32_e32 v23, v24, v21
	v_fma_f32 v20, -v20, v23, v22
	v_div_scale_f32 v22, s[18:19], v18, v18, 1.0
	v_rcp_f32_e32 v24, v22
	v_div_fmas_f32 v20, v20, v21, v23
	v_div_fixup_f32 v19, v20, v19, 1.0
	v_fma_f32 v20, -v22, v24, 1.0
	v_fmac_f32_e32 v24, v20, v24
	v_div_scale_f32 v20, vcc, 1.0, v18, 1.0
	v_mul_f32_e32 v21, v20, v24
	v_fma_f32 v23, -v22, v21, v20
	v_fmac_f32_e32 v21, v23, v24
	v_fma_f32 v20, -v22, v21, v20
	v_div_scale_f32 v22, s[18:19], v17, v17, 1.0
	v_rcp_f32_e32 v23, v22
	v_div_fmas_f32 v20, v20, v24, v21
	v_div_fixup_f32 v18, v20, v18, 1.0
	v_fma_f32 v20, -v22, v23, 1.0
	v_fmac_f32_e32 v23, v20, v23
	v_div_scale_f32 v20, vcc, 1.0, v17, 1.0
	v_mul_f32_e32 v21, v20, v23
	v_fma_f32 v24, -v22, v21, v20
	v_fmac_f32_e32 v21, v24, v23
	v_fma_f32 v20, -v22, v21, v20
	v_div_scale_f32 v22, s[18:19], v16, v16, 1.0
	v_rcp_f32_e32 v24, v22
	v_div_fmas_f32 v20, v20, v23, v21
	v_div_fixup_f32 v20, v20, v17, 1.0
	v_fma_f32 v17, -v22, v24, 1.0
	v_fmac_f32_e32 v24, v17, v24
	v_div_scale_f32 v17, vcc, 1.0, v16, 1.0
	v_mul_f32_e32 v21, v17, v24
	v_fma_f32 v23, -v22, v21, v17
	v_fmac_f32_e32 v21, v23, v24
	v_fma_f32 v17, -v22, v21, v17
	v_div_fmas_f32 v17, v17, v24, v21
	v_div_fixup_f32 v21, v17, v16, 1.0
	v_mul_f32_e32 v12, v12, v21
	v_mul_f32_e32 v4, v4, v21
	v_mul_f32_e32 v0, v0, v21
	v_mul_f32_e32 v8, v8, v21
	v_mul_f32_e32 v13, v13, v20
	v_mul_f32_e32 v5, v5, v20
	v_mul_f32_e32 v1, v1, v20
	v_mul_f32_e32 v9, v9, v20
	v_mul_f32_e32 v14, v14, v18
	v_mul_f32_e32 v6, v6, v18
	v_mul_f32_e32 v2, v2, v18
	v_mul_f32_e32 v10, v10, v18
	v_mul_f32_e32 v15, v15, v19
	v_mul_f32_e32 v7, v7, v19
	v_mul_f32_e32 v3, v3, v19
	v_mul_f32_e32 v11, v11, v19
	v_lshl_add_u32 v25, v116, 1, s47
	v_cvt_pk_bf16_f32 v12, v12, v4
	v_cvt_pk_bf16_f32 v0, v0, v8
	v_cvt_pk_bf16_f32 v13, v13, v5
	v_cvt_pk_bf16_f32 v1, v1, v9
	v_cvt_pk_bf16_f32 v14, v14, v6
	v_cvt_pk_bf16_f32 v2, v2, v10
	v_cvt_pk_bf16_f32 v15, v15, v7
	v_cvt_pk_bf16_f32 v3, v3, v11
	ds_write_b16 v25, v12 offset:1024
	ds_write_b16_d16_hi v25, v12 offset:1056
	ds_write_b16 v25, v0 offset:1088
	ds_write_b16_d16_hi v25, v0 offset:1120
	ds_write_b16 v25, v13 offset:1152
	ds_write_b16_d16_hi v25, v13 offset:1184
	ds_write_b16 v25, v1 offset:1216
	ds_write_b16_d16_hi v25, v1 offset:1248
	ds_write_b16 v25, v14 offset:1280
	ds_write_b16_d16_hi v25, v14 offset:1312
	ds_write_b16 v25, v2 offset:1344
	ds_write_b16_d16_hi v25, v2 offset:1376
	ds_write_b16 v25, v15 offset:1408
	ds_write_b16_d16_hi v25, v15 offset:1440
	ds_write_b16 v25, v3 offset:1472
	ds_write_b16_d16_hi v25, v3 offset:1504
	s_mov_b32 exec_lo, -1
	s_mov_b32 exec_hi, 0
	v_lshl_add_u32 v26, v117, 4, s47
	v_lshlrev_b32_e32 v27, 4, v117
	s_add_u32 s18, s16, s14
	s_addc_u32 s19, s17, s15
	ds_read_b128 v[28:31], v26 offset:1024
	s_waitcnt lgkmcnt(0)
	global_store_dwordx4 v27, v[28:31], s[18:19]
	s_branch .LBB0_1251
